# v_c12 + first-half L2 prefetch of Q rows and first K/V tile at attention phase start (before the short-conv part)
# speedup vs baseline: 1.0040x; 1.0037x over previous
; __device__ __forceinline__ void shortconv_phase(const bf16* PROJ, const float* cw  , bf16* MIX, int G, int wave_s) {
;     ...
;     const int c8 = (tid_ & 127) * 8;
;     const f32x4 wa0 = *(const f32x4*)(cw + c8), wb0 = *(const f32x4*)(cw + c8 + 4), wa1 = *(const f32x4*)(cw + 1024 + c8), wb1 = *(const f32x4*)(cw + 1024 + c8 + 4), wa2 = *(const f32x4*)(cw + 2048 + c8), wb2 = *(const f32x4*)(cw + 2048 + c8 + 4);
;     for (int q = (int)blockIdx.x * 4 + (tid_ >> 7); q < MTOK / 4; q += G * 4) {
;         const int m0 = q * 4, t0 = m0 & (SEQ - 1);
;         v4u g[6], x[6], gb[4];
; #pragma unroll
;         for (int r = 0; r < 6; ++r) { const bool ok = (t0 + r - 2 >= 0); const bf16* row = PROJ + (size_t)(m0 + r - 2) * PLD + c8;
;             g[r] = ok ? *(const v4u*)(row + 1024) : (v4u){0u, 0u, 0u, 0u}; x[r] = ok ? *(const v4u*)(row + 2048) : (v4u){0u, 0u, 0u, 0u}; }
; __device__ __forceinline__ void attn_phase(LAS unsigned char* lds, const bf16* PROJ, bf16* MIX, const float* lq1, const float* lk1, const float* lq2, const float* lk2,
;                                            const float* norm_g, float lambda_init, int G, int wave_s) {
;     ...
;     for (int u0 = blockIdx.x; u0 < 256; u0 += G) {
;         const int u = (G == 256) ? (((u0 & 7) << 5) | (u0 >> 3)) : u0;
;         const int b = u >> 6, h = (u >> 4) & 3, p = u & 15;
;         const float sl2 = exp2f(-2.0f * (float)(h + 1)) * LOG2E;
;         const bf16* base = PROJ + (size_t)b * SEQ * PLD;
;         for (int half = 0; half < 2; ++half) {
;             const int qb = half ? 31 - p : p;
;             const int qloc = 16 * wq + l15;
;             bf16x8 qf[4];
;             { const bf16* qp = base + (size_t)(64 * qb + qloc) * PLD + 3072 + h * 256 + mi * 128 + 8 * q4;
; #pragma unroll
;               for (int sk = 0; sk < 4; ++sk) qf[sk] = *(const bf16x8*)(qp + 32 * sk); }
.LBB0_871:
	s_andn2_b64 vcc, exec, s[0:1]
	s_cbranch_vccnz .LBB0_954
	s_mov_b64 s[8:9], s[90:91]
	s_load_dword s36, s[78:79], 0x0
	s_load_dwordx2 s[0:1], s[8:9], 0x118
	v_readlane_b32 s10, v253, 48
	s_waitcnt lgkmcnt(0)
	s_mov_b32 s37, s36
	v_mbcnt_lo_u32_b32 v0, -1, 0
	v_mbcnt_hi_u32_b32 v0, -1, v0
	s_add_u32 s6, s0, 0x1ee00000
	v_add_u32_e32 v0, s89, v0
	s_addc_u32 s7, s1, 0
	s_add_u32 s0, s0, 0x24e00000
	s_waitcnt vmcnt(0)
	v_ashrrev_i32_e32 v26, 7, v0
	v_add_u32_e32 v106, s10, v26
	s_movk_i32 s10, 0x800
	s_addc_u32 s1, s1, 0
	v_readlane_b32 s12, v253, 0
	s_and_b32 s13, s12, 7
	s_lshl_b32 s13, s13, 5
	s_lshr_b32 s12, s12, 3
	s_or_b32 s12, s12, s13
	s_lshr_b32 s13, s12, 6
	s_bfe_u32 s14, s12, 0x20004
	s_and_b32 s15, s12, 15
	s_mul_i32 s100, s13, 0x1800000
	s_mul_i32 s15, s15, 0xc0000
	s_lshl_b32 s14, s14, 9
	s_add_u32 s100, s100, s15
	s_add_u32 s100, s100, s14
	s_add_u32 s100, s100, 0x1800
	s_add_u32 s100, s6, s100
	s_addc_u32 s101, s7, 0
	v_mul_u32_u24_e32 v3, 0xaaab, v0
	v_lshrrev_b32_e32 v3, 19, v3
	v_mul_u32_u24_e32 v4, 12, v3
	v_sub_u32_e32 v2, v0, v4
	v_mul_u32_u24_e32 v3, 0x3000, v3
	v_lshl_add_u32 v3, v2, 7, v3
	v_lshrrev_b32_e32 v2, 2, v2
	v_mul_u32_u24_e32 v2, 0x600, v2
	v_add_u32_e32 v3, v3, v2
	global_load_dword v250, v3, s[100:101]
	s_cmpk_ge_u32 s89, 0x100
	s_cbranch_scc1 .Lattn_pf0_done
	v_add_u32_e32 v5, 0x200, v0
	v_mul_u32_u24_e32 v3, 0xaaab, v5
	v_lshrrev_b32_e32 v3, 19, v3
	v_mul_u32_u24_e32 v4, 12, v3
	v_sub_u32_e32 v2, v5, v4
	v_mul_u32_u24_e32 v3, 0x3000, v3
	v_lshl_add_u32 v3, v2, 7, v3
	v_lshrrev_b32_e32 v2, 2, v2
	v_mul_u32_u24_e32 v2, 0x600, v2
	v_add_u32_e32 v3, v3, v2
	global_load_dword v250, v3, s[100:101]
.Lattn_pf0_done:
	v_cmp_gt_i32_e32 vcc, s10, v106
	s_and_saveexec_b64 s[10:11], vcc
	s_cbranch_execz .LBB0_879
	s_load_dwordx2 s[12:13], s[8:9], 0xe0
	v_readlane_b32 s14, v254, 57
	v_readlane_b32 s15, v254, 58
	s_mul_i32 s80, s14, 0xc00
	v_lshlrev_b32_e32 v0, 3, v0
	s_lshl_b64 s[14:15], s[80:81], 2
	v_and_b32_e32 v27, 0x3f8, v0
	s_waitcnt lgkmcnt(0)
	s_add_u32 s12, s12, s14
	s_addc_u32 s13, s13, s15
	v_lshlrev_b32_e32 v0, 2, v27
	v_lshl_add_u64 v[10:11], s[12:13], 0, v[0:1]
	s_mov_b64 s[14:15], 0x2000
	v_add_co_u32_e32 v2, vcc, s33, v10
	v_lshl_add_u64 v[6:7], v[10:11], 0, s[14:15]
	s_nop 0
	v_addc_co_u32_e32 v3, vcc, 0, v11, vcc
	s_mov_b64 s[14:15], 0x1000
	v_lshl_add_u64 v[14:15], v[10:11], 0, s[14:15]
	v_add_co_u32_e32 v10, vcc, s75, v10
	global_load_dwordx4 v[2:5], v[2:3], off
	s_nop 0
	global_load_dwordx4 v[6:9], v[6:7], off offset:16
	v_addc_co_u32_e32 v11, vcc, 0, v11, vcc
	global_load_dwordx4 v[10:13], v[10:11], off
	s_nop 0
	global_load_dwordx4 v[14:17], v[14:15], off offset:16
	s_nop 0
	global_load_dwordx4 v[18:21], v0, s[12:13]
	global_load_dwordx4 v[22:25], v0, s[12:13] offset:16
	v_lshlrev_b32_e32 v0, 1, v27
	v_readlane_b32 s12, v254, 31
	v_lshl_add_u64 v[90:91], s[6:7], 0, v[0:1]
	v_lshl_add_u64 v[92:93], s[0:1], 0, v[0:1]
	s_lshl_b32 s16, s37, 2
	v_lshl_add_u32 v94, v26, 2, s12
	s_lshl_b32 s17, s37, 4
	s_mov_b64 s[12:13], 0
	s_branch .LBB0_875
